# speedup vs baseline: 1.0116x; 1.0015x over previous
; #define LAS __attribute__((address_space(3)))
; #define MFMA32(a_, b_, c_) __builtin_amdgcn_mfma_f32_32x32x16_bf16((a_), (b_), (c_), 0, 0, 0)
; __device__ __forceinline__ void gmlp_fast(KArgs ap, int l, LAS unsigned char* lds, const Ctx cx) {
;     ...
;             for (int ks = 0; ks <= 2 * tb + 1; ++ks) {
;                 const int s0 = 16 * ks + 8 * hh;
;                 const f32x4 w0 = wn0, w1 = wn1;
;                 if (ks < 2 * tb + 1) { wn0 = *(const f32x4*)(wrow + 16 * (ks + 1)); wn1 = *(const f32x4*)(wrow + 16 * (ks + 1) + 4); }
;                 float f[8] = {w0.x, w0.y, w0.z, w0.w, w1.x, w1.y, w1.z, w1.w};
; #pragma unroll
;                 for (int j = 0; j < 8; ++j) f[j] = (s0 + j <= tl) ? f[j] : 0.f;
;                 const bf16x8 bfrag = pack8(f[0], f[1], f[2], f[3], f[4], f[5], f[6], f[7]);
; #pragma unroll
;                 for (int ht = 0; ht < 4; ++ht) { const bf16x8 afrag = *(const LAS bf16x8*)(VT + (gl * 128 + ht * 32 + r) * 272 + s0 * 2); acc[ht] = MFMA32(afrag, bfrag, acc[ht]); }
;             }
.LBB0_164:
	ds_read_b128 v[200:203], v93
	ds_read_b128 v[204:207], v93 offset:8704
	ds_read_b128 v[208:211], v93 offset:17408
	ds_read_b128 v[212:215], v93 offset:26112
	v_add_u32_e32 v108, s13, v84
	v_cmp_le_u32_e32 vcc, v108, v80
	v_add_u32_e32 v109, 2, v108
	s_add_i32 s21, s21, 1
	v_cndmask_b32_e32 v76, 0, v76, vcc
	v_cmp_lt_u32_e32 vcc, v108, v80
	s_add_i32 s13, s13, 16
	v_lshl_add_u64 v[98:99], v[98:99], 0, 64
	v_cndmask_b32_e32 v77, 0, v77, vcc
	v_cmp_le_u32_e32 vcc, v109, v80
	v_add_u32_e32 v109, 3, v108
	s_cmp_eq_u32 s40, s13
	v_cndmask_b32_e32 v78, 0, v78, vcc
	v_cmp_le_u32_e32 vcc, v109, v80
	v_add_u32_e32 v109, 4, v108
	s_nop 0
	v_cndmask_b32_e32 v79, 0, v79, vcc
	v_cmp_le_u32_e32 vcc, v109, v80
	s_nop 1
	v_cndmask_b32_e32 v109, 0, v72, vcc
	v_add_u32_e32 v72, 5, v108
	v_cmp_le_u32_e32 vcc, v72, v80
	v_add_u32_e32 v72, 6, v108
	s_nop 0
	v_cndmask_b32_e32 v110, 0, v73, vcc
	v_cmp_le_u32_e32 vcc, v72, v80
	v_add_u32_e32 v72, 7, v108
	s_nop 0
	v_cndmask_b32_e32 v111, 0, v74, vcc
	v_cmp_le_u32_e32 vcc, v72, v80
	s_nop 1
	v_cndmask_b32_e32 v108, 0, v75, vcc
	s_nop 1
	v_cvt_pk_bf16_f32 v72, v76, v77
	v_cvt_pk_bf16_f32 v73, v78, v79
	v_cvt_pk_bf16_f32 v74, v109, v110
	v_cvt_pk_bf16_f32 v75, v111, v108
	s_nop 1
	s_waitcnt lgkmcnt(3)
	v_mfma_f32_32x32x16_bf16 v[48:63], v[200:203], v[72:75], v[48:63]
	s_waitcnt lgkmcnt(2)
	v_mfma_f32_32x32x16_bf16 v[32:47], v[204:207], v[72:75], v[32:47]
	s_waitcnt lgkmcnt(1)
	v_mfma_f32_32x32x16_bf16 v[16:31], v[208:211], v[72:75], v[16:31]
	v_add_u32_e32 v93, 32, v93
	s_waitcnt lgkmcnt(0)
	v_mfma_f32_32x32x16_bf16 v[0:15], v[212:215], v[72:75], v[0:15]
	s_waitcnt vmcnt(1)
	v_mov_b64_e32 v[74:75], v[70:71]
	s_waitcnt vmcnt(0)
	v_mov_b64_e32 v[78:79], v[66:67]
	v_mov_b64_e32 v[72:73], v[68:69]
	v_mov_b64_e32 v[76:77], v[64:65]
	s_cbranch_scc1 .LBB0_160
